# ssd_pass2 epilogue: 12 of the group-norm weight loads issued at the very start of the epilogue; idle vmcnt part of the first wait dropped
# speedup vs baseline: 1.0034x; 1.0034x over previous
.LBB0_220:
	s_waitcnt vmcnt(9)
	v_lshlrev_b32_e32 v248, 2, v166
	v_readlane_b32 s2, v254, 32
	v_readlane_b32 s3, v254, 33
	s_lshl_b32 s9, s17, 2
	s_add_u32 s2, s2, s9
	s_addc_u32 s3, s3, 0
	global_load_dwordx4 v[204:207], v248, s[2:3] offset:16
	global_load_dwordx4 v[208:211], v248, s[2:3]
	global_load_dwordx4 v[212:215], v248, s[2:3] offset:272
	global_load_dwordx4 v[216:219], v248, s[2:3] offset:256
	global_load_dwordx4 v[220:223], v248, s[2:3] offset:528
	global_load_dwordx4 v[224:227], v248, s[2:3] offset:512
	global_load_dwordx4 v[228:231], v248, s[2:3] offset:784
	global_load_dwordx4 v[232:235], v248, s[2:3] offset:768
	global_load_dwordx4 v[236:239], v248, s[2:3] offset:1040
	global_load_dwordx4 v[240:243], v248, s[2:3] offset:1024
	global_load_dwordx4 v[146:149], v248, s[2:3] offset:1296
	global_load_dwordx4 v[150:153], v248, s[2:3] offset:1280
	v_readlane_b32 s0, v251, 24
	v_add_u32_e32 v108, s19, v169
	v_ashrrev_i32_e32 v109, 31, v108
	v_lshlrev_b64 v[108:109], 12, v[108:109]
	v_readlane_b32 s1, v251, 25
	s_ashr_i32 s35, s34, 31
	v_readlane_b32 s40, v254, 20
	s_lshl_b32 s28, s17, 1
	s_lshl_b64 s[0:1], s[34:35], 2
	v_readlane_b32 s50, v254, 30
	v_mov_b32_e32 v133, v157
	v_readlane_b32 s51, v254, 31
	s_add_u32 s0, s50, s0
	s_addc_u32 s1, s51, s1
	v_cmp_lt_i32_e32 vcc, v188, v187
	v_mov_b32_e32 v110, v160
	v_readlane_b32 s0, v253, 62
	s_mov_b32 s56, 0x800000
	v_readlane_b32 s52, v254, 32
	v_add3_u32 v112, s0, v173, v137
	ds_read2_b64 v[104:107], v112 offset1:4
	v_add_u32_e32 v113, 0x1000, v112
	v_add_u32_e32 v118, 0x1800, v112
	s_lshl_b32 s0, s20, 2
	s_add_i32 s0, s0, 16
	s_waitcnt lgkmcnt(0)
	v_lshlrev_b32_e32 v32, 16, v104
	v_readlane_b32 s53, v254, 33
	v_readlane_b32 s8, v251, 51
	v_readlane_b32 s9, v251, 52
	v_readlane_b32 s72, v254, 41
	v_readlane_b32 s54, v254, 34
	v_readlane_b32 s55, v254, 35
	v_readlane_b32 s70, v254, 39
	v_readlane_b32 s73, v254, 42
	v_readlane_b32 s74, v254, 44
	v_readlane_b32 s76, v254, 46
	v_readlane_b32 s78, v254, 48
	v_readlane_b32 s82, v254, 52
	v_readlane_b32 s60, v254, 54
	v_readlane_b32 s62, v254, 56
	v_readlane_b32 s64, v254, 58
	v_readlane_b32 s66, v254, 60
	s_movk_i32 s68, 0x2040
	v_readlane_b32 s57, v254, 36
	v_readlane_b32 s58, v254, 37
	v_readlane_b32 s59, v254, 38
	v_readlane_b32 s71, v254, 40
	v_readlane_b32 s69, v254, 43
	v_readlane_b32 s75, v254, 45
	v_readlane_b32 s77, v254, 47
	v_readlane_b32 s79, v254, 49
	v_readlane_b32 s80, v254, 50
	v_readlane_b32 s81, v254, 51
	v_readlane_b32 s83, v254, 53
	v_readlane_b32 s61, v254, 55
	v_readlane_b32 s63, v254, 57
	v_readlane_b32 s65, v254, 59
	v_readlane_b32 s67, v254, 61
	s_movk_i32 s73, 0xf5
	s_movk_i32 s55, 0xfff
	s_mov_b32 s54, 0xf0c0
	v_readlane_b32 s41, v254, 21
	v_readlane_b32 s42, v254, 22
	v_readlane_b32 s43, v254, 23
	v_readlane_b32 s44, v254, 24
	v_readlane_b32 s45, v254, 25
	v_readlane_b32 s46, v254, 26
	v_readlane_b32 s47, v254, 27
	v_readlane_b32 s48, v254, 28
	v_readlane_b32 s49, v254, 29
	v_fma_f32 v111, v110, v32, v40
	v_and_b32_e32 v32, 0xffff0000, v104
	v_fma_f32 v104, v110, v32, v41
	v_lshlrev_b32_e32 v32, 16, v105
	v_fma_f32 v42, v110, v32, v42
	v_and_b32_e32 v32, 0xffff0000, v105
	v_add_u32_e32 v105, 0x800, v112
	ds_read2_b64 v[34:37], v105 offset0:32 offset1:36
	ds_read2_b64 v[38:41], v113 offset0:64 offset1:68
	v_fmac_f32_e32 v43, v110, v32
	ds_read2_b64 v[114:117], v105 offset0:40 offset1:44
	s_waitcnt lgkmcnt(2)
	v_lshlrev_b32_e32 v32, 16, v34
	v_fma_f32 v48, v110, v32, v48
	v_and_b32_e32 v32, 0xffff0000, v34
	v_fma_f32 v49, v110, v32, v49
	v_lshlrev_b32_e32 v32, 16, v35
	v_fma_f32 v50, v110, v32, v50
	v_and_b32_e32 v32, 0xffff0000, v35
	v_fmac_f32_e32 v51, v110, v32
	s_waitcnt lgkmcnt(1)
	v_lshlrev_b32_e32 v32, 16, v38
	v_fma_f32 v44, v110, v32, v44
	v_and_b32_e32 v32, 0xffff0000, v38
	v_fma_f32 v38, v110, v32, v45
	v_lshlrev_b32_e32 v32, 16, v39
	v_fma_f32 v45, v110, v32, v46
	v_and_b32_e32 v32, 0xffff0000, v39
	v_fmac_f32_e32 v47, v110, v32
	ds_read2_b64 v[32:35], v118 offset0:96 offset1:100
	ds_read2_b64 v[118:121], v118 offset0:104 offset1:108
	s_waitcnt lgkmcnt(1)
	v_lshlrev_b32_e32 v46, 16, v33
	v_fma_f32 v46, v110, v46, v54
	v_and_b32_e32 v33, 0xffff0000, v33
	v_and_b32_e32 v54, 0xffff0000, v107
	v_lshlrev_b32_e32 v39, 16, v32
	v_fmac_f32_e32 v55, v110, v33
	v_lshlrev_b32_e32 v33, 16, v106
	v_fmac_f32_e32 v59, v110, v54
	v_lshlrev_b32_e32 v54, 16, v36
	v_and_b32_e32 v36, 0xffff0000, v36
	v_fma_f32 v39, v110, v39, v52
	v_fma_f32 v33, v110, v33, v56
	v_and_b32_e32 v52, 0xffff0000, v106
	v_fma_f32 v56, v110, v36, v61
	v_lshlrev_b32_e32 v36, 16, v37
	v_and_b32_e32 v32, 0xffff0000, v32
	v_fma_f32 v52, v110, v52, v57
	v_fma_f32 v57, v110, v36, v62
	v_and_b32_e32 v36, 0xffff0000, v37
	v_fma_f32 v32, v110, v32, v53
	v_lshlrev_b32_e32 v53, 16, v107
	v_fmac_f32_e32 v63, v110, v36
	v_lshlrev_b32_e32 v36, 16, v40
	v_fma_f32 v53, v110, v53, v58
	v_fma_f32 v58, v110, v36, v64
	v_and_b32_e32 v36, 0xffff0000, v40
	v_fma_f32 v40, v110, v36, v65
	v_lshlrev_b32_e32 v36, 16, v41
	v_fma_f32 v54, v110, v54, v60
	v_fma_f32 v60, v110, v36, v66
	v_and_b32_e32 v36, 0xffff0000, v41
	v_fmac_f32_e32 v67, v110, v36
	v_lshlrev_b32_e32 v36, 16, v34
	v_and_b32_e32 v34, 0xffff0000, v34
	v_fma_f32 v61, v110, v34, v81
	v_lshlrev_b32_e32 v34, 16, v35
	v_fma_f32 v62, v110, v34, v82
	v_and_b32_e32 v34, 0xffff0000, v35
	v_fma_f32 v41, v110, v36, v80
	v_fmac_f32_e32 v83, v110, v34
	ds_read2_b64 v[34:37], v112 offset0:8 offset1:12
	v_and_b32_e32 v66, 0xffff0000, v114
	v_fma_f32 v66, v110, v66, v73
	v_and_b32_e32 v73, 0xffff0000, v115
	v_and_b32_e32 v80, 0xffff0000, v116
	s_waitcnt lgkmcnt(0)
	v_lshlrev_b32_e32 v65, 16, v35
	v_fma_f32 v65, v110, v65, v78
	v_lshlrev_b32_e32 v78, 16, v37
	v_fma_f32 v78, v110, v78, v90
	v_and_b32_e32 v37, 0xffff0000, v37
	v_and_b32_e32 v90, 0xffff0000, v121
	v_and_b32_e32 v35, 0xffff0000, v35
	v_fmac_f32_e32 v91, v110, v37
	v_lshlrev_b32_e32 v37, 16, v116
	v_fmac_f32_e32 v103, v110, v90
	v_lshl_add_u32 v90, v171, 2, s0
	s_movk_i32 s0, 0x2040
	v_fmac_f32_e32 v79, v110, v35
	v_lshlrev_b32_e32 v35, 16, v114
	v_fma_f32 v37, v110, v37, v92
	v_mad_u32_u24 v92, v172, s0, v90
	v_fma_f32 v35, v110, v35, v72
	v_lshlrev_b32_e32 v72, 16, v115
	ds_read2_b64 v[112:115], v113 offset0:72 offset1:76
	s_waitcnt lgkmcnt(0)
	s_barrier
	ds_write2_b32 v92, v111, v48 offset1:16
	v_add_u32_e32 v48, 0x800, v92
	ds_write2_b32 v48, v104, v49 offset0:4 offset1:20
	v_add_u32_e32 v49, 0x1000, v92
	ds_write2_b32 v49, v42, v50 offset0:8 offset1:24
	v_add_u32_e32 v42, 0x1800, v92
	ds_write2_b32 v42, v43, v51 offset0:12 offset1:28
	ds_write2_b32 v92, v44, v39 offset0:32 offset1:48
	ds_write2_b32 v48, v38, v32 offset0:36 offset1:52
	ds_write2_b32 v49, v45, v46 offset0:40 offset1:56
	ds_write2_b32 v42, v47, v55 offset0:44 offset1:60
	v_add_u32_e32 v32, 0x8000, v92
	ds_write2_b32 v32, v33, v54 offset0:64 offset1:80
	v_add_u32_e32 v33, 0x8800, v92
	v_add_u32_e32 v38, 0x9000, v92
	v_add_u32_e32 v39, 0x9800, v92
	ds_write2_b32 v33, v52, v56 offset0:68 offset1:84
	ds_write2_b32 v38, v53, v57 offset0:72 offset1:88
	ds_write2_b32 v39, v59, v63 offset0:76 offset1:92
	ds_write2_b32 v32, v58, v41 offset0:96 offset1:112
	ds_write2_b32 v33, v40, v61 offset0:100 offset1:116
	ds_write2_b32 v38, v60, v62 offset0:104 offset1:120
	ds_write2_b32 v39, v67, v83 offset0:108 offset1:124
	v_mov_b32_e32 v32, 0x10200
	v_lshlrev_b32_e32 v64, 16, v34
	v_mad_u32_u24 v32, v172, s0, v32
	v_fma_f32 v64, v110, v64, v76
	v_add_u32_e32 v33, v90, v32
	ds_write_b32 v33, v64
	v_mov_b32_e32 v33, 0x10a10
	v_and_b32_e32 v34, 0xffff0000, v34
	v_mad_u32_u24 v33, v172, s0, v33
	v_fma_f32 v34, v110, v34, v77
	v_add_u32_e32 v38, v90, v33
	ds_write_b32 v38, v34
	v_mov_b32_e32 v34, 0x11220
	v_mad_u32_u24 v34, v172, s0, v34
	v_add_u32_e32 v38, v90, v34
	ds_write_b32 v38, v65
	v_mov_b32_e32 v38, 0x11a30
	v_mad_u32_u24 v38, v172, s0, v38
	v_fmac_f32_e32 v75, v110, v73
	v_lshlrev_b32_e32 v73, 16, v112
	v_fma_f32 v80, v110, v80, v93
	v_add_u32_e32 v93, 64, v90
	v_add_u32_e32 v39, v90, v38
	v_fma_f32 v68, v110, v73, v68
	v_and_b32_e32 v73, 0xffff0000, v112
	ds_write_b32 v39, v79
	v_add_u32_e32 v39, v93, v32
	v_fma_f32 v69, v110, v73, v69
	v_lshlrev_b32_e32 v73, 16, v113
	ds_write_b32 v39, v35
	v_add_u32_e32 v35, v93, v33
	v_fma_f32 v72, v110, v72, v74
	v_fma_f32 v70, v110, v73, v70
	v_and_b32_e32 v73, 0xffff0000, v113
	ds_write_b32 v35, v66
	v_add_u32_e32 v35, v93, v34
	v_fmac_f32_e32 v71, v110, v73
	v_lshlrev_b32_e32 v73, 16, v118
	v_add_u32_e32 v43, 0x80, v90
	v_add_u32_e32 v50, 0xc0, v90
	ds_write_b32 v35, v72
	v_add_u32_e32 v35, v93, v38
	v_fma_f32 v73, v110, v73, v84
	v_and_b32_e32 v74, 0xffff0000, v118
	ds_write_b32 v35, v75
	v_add_u32_e32 v35, v43, v32
	v_add_u32_e32 v32, v50, v32
	v_fma_f32 v74, v110, v74, v85
	v_lshlrev_b32_e32 v76, 16, v119
	ds_write_b32 v32, v73
	v_add_u32_e32 v32, v50, v33
	v_fma_f32 v76, v110, v76, v86
	v_and_b32_e32 v77, 0xffff0000, v119
	ds_write_b32 v32, v74
	v_add_u32_e32 v32, v50, v34
	v_fmac_f32_e32 v87, v110, v77
	ds_write_b32 v32, v76
	v_add_u32_e32 v32, v50, v38
	ds_write_b32 v32, v87
	v_mov_b32_e32 v32, 0x18300
	v_lshlrev_b32_e32 v77, 16, v36
	v_mad_u32_u24 v32, v172, s0, v32
	v_fma_f32 v77, v110, v77, v88
	ds_write_b32 v35, v68
	v_add_u32_e32 v35, v43, v33
	v_add_u32_e32 v33, v90, v32
	ds_write_b32 v33, v77
	v_mov_b32_e32 v33, 0x18b10
	v_and_b32_e32 v36, 0xffff0000, v36
	v_mad_u32_u24 v33, v172, s0, v33
	v_fma_f32 v36, v110, v36, v89
	ds_write_b32 v35, v69
	v_add_u32_e32 v35, v43, v34
	v_add_u32_e32 v34, v90, v33
	ds_write_b32 v34, v36
	v_mov_b32_e32 v34, 0x19320
	ds_write_b32 v35, v70
	v_add_u32_e32 v35, v43, v38
	v_mad_u32_u24 v34, v172, s0, v34
	ds_write_b32 v35, v71
	v_add_u32_e32 v35, v90, v34
	ds_write_b32 v35, v78
	v_mad_u32_u24 v35, v172, s0, v198
	v_add_u32_e32 v36, v90, v35
	ds_write_b32 v36, v91
	v_add_u32_e32 v36, v93, v32
	v_lshlrev_b32_e32 v81, 16, v117
	ds_write_b32 v36, v37
	v_add_u32_e32 v36, v93, v33
	v_fma_f32 v81, v110, v81, v94
	v_and_b32_e32 v82, 0xffff0000, v117
	v_and_b32_e32 v86, 0xffff0000, v115
	ds_write_b32 v36, v80
	v_add_u32_e32 v36, v93, v34
	v_fmac_f32_e32 v95, v110, v82
	v_fmac_f32_e32 v99, v110, v86
	v_lshlrev_b32_e32 v86, 16, v120
	ds_write_b32 v36, v81
	v_add_u32_e32 v36, v93, v35
	v_fma_f32 v86, v110, v86, v100
	v_and_b32_e32 v88, 0xffff0000, v120
	ds_write_b32 v36, v95
	v_add_u32_e32 v36, v43, v32
	v_add_u32_e32 v32, v50, v32
	v_lshlrev_b32_e32 v82, 16, v114
	v_fma_f32 v88, v110, v88, v101
	v_lshlrev_b32_e32 v89, 16, v121
	ds_write_b32 v32, v86
	v_add_u32_e32 v32, v50, v33
	v_fma_f32 v82, v110, v82, v96
	v_and_b32_e32 v84, 0xffff0000, v114
	v_fma_f32 v89, v110, v89, v102
	ds_write_b32 v32, v88
	v_add_u32_e32 v32, v50, v34
	v_fma_f32 v84, v110, v84, v97
	v_lshlrev_b32_e32 v85, 16, v115
	ds_write_b32 v36, v82
	v_add_u32_e32 v36, v43, v33
	ds_write_b32 v32, v89
	v_add_u32_e32 v32, v50, v35
	s_movk_i32 s0, 0x810
	v_fma_f32 v85, v110, v85, v98
	ds_write_b32 v36, v84
	v_add_u32_e32 v36, v43, v34
	ds_write_b32 v32, v103
	v_mul_lo_u32 v33, v169, s0
	v_lshlrev_b32_e32 v32, 2, v166
	ds_write_b32 v36, v85
	v_add_u32_e32 v36, v43, v35
	v_add3_u32 v76, 16, v33, v32
	ds_write_b32 v36, v99
	s_waitcnt lgkmcnt(0)
	s_barrier
	ds_read_b128 v[34:37], v76
	ds_read_b128 v[38:41], v76 offset:16
	s_waitcnt vmcnt(0)
	s_lshl_b32 s2, s17, 2
	s_add_u32 s2, s52, s2
	s_addc_u32 s3, s53, 0
	global_load_dwordx4 v[168:171], v32, s[2:3] offset:1552
	global_load_dwordx4 v[172:175], v32, s[2:3] offset:1536
	global_load_dwordx4 v[176:179], v32, s[2:3] offset:1808
	v_lshlrev_b32_e32 v33, 16, v28
	v_and_b32_e32 v28, 0xffff0000, v28
	v_lshlrev_b32_e32 v42, 16, v29
	s_waitcnt lgkmcnt(1)
	v_mul_f32_e32 v72, v35, v28
	v_mul_f32_e32 v73, v34, v33
	v_mul_f32_e32 v77, v72, v72
	v_and_b32_e32 v29, 0xffff0000, v29
	v_mul_f32_e32 v71, v36, v42
	v_fmac_f32_e32 v77, v73, v73
	v_lshlrev_b32_e32 v43, 16, v30
	v_and_b32_e32 v30, 0xffff0000, v30
	v_lshlrev_b32_e32 v44, 16, v31
	v_and_b32_e32 v31, 0xffff0000, v31
	v_mul_f32_e32 v70, v37, v29
	v_fmac_f32_e32 v77, v71, v71
	s_waitcnt lgkmcnt(0)
	v_mul_f32_e32 v69, v38, v43
	v_mul_f32_e32 v68, v39, v30
	v_mul_f32_e32 v65, v41, v31
	v_fmac_f32_e32 v77, v70, v70
	ds_read_b128 v[28:31], v76 offset:256
	ds_read_b128 v[34:37], v76 offset:272
	v_fmac_f32_e32 v77, v69, v69
	v_mul_f32_e32 v67, v40, v44
	v_fmac_f32_e32 v77, v68, v68
	v_fmac_f32_e32 v77, v67, v67
	v_lshlrev_b32_e32 v33, 16, v24
	v_fmac_f32_e32 v77, v65, v65
	v_and_b32_e32 v24, 0xffff0000, v24
	s_waitcnt lgkmcnt(1)
	v_mul_f32_e32 v66, v28, v33
	v_lshlrev_b32_e32 v38, 16, v25
	v_mul_f32_e32 v63, v29, v24
	v_fmac_f32_e32 v77, v66, v66
	v_and_b32_e32 v25, 0xffff0000, v25
	v_mul_f32_e32 v60, v30, v38
	v_fmac_f32_e32 v77, v63, v63
	v_lshlrev_b32_e32 v39, 16, v26
	v_and_b32_e32 v26, 0xffff0000, v26
	v_lshlrev_b32_e32 v40, 16, v27
	v_and_b32_e32 v27, 0xffff0000, v27
	v_mul_f32_e32 v56, v31, v25
	v_fmac_f32_e32 v77, v60, v60
	s_waitcnt lgkmcnt(0)
	v_mul_f32_e32 v51, v34, v39
	v_mul_f32_e32 v45, v35, v26
	v_mul_f32_e32 v35, v37, v27
	v_fmac_f32_e32 v77, v56, v56
	ds_read_b128 v[24:27], v76 offset:512
	ds_read_b128 v[28:31], v76 offset:528
	v_fmac_f32_e32 v77, v51, v51
	v_mul_f32_e32 v40, v36, v40
	v_fmac_f32_e32 v77, v45, v45
	v_fmac_f32_e32 v77, v40, v40
	v_lshlrev_b32_e32 v33, 16, v20
	v_fmac_f32_e32 v77, v35, v35
	v_and_b32_e32 v20, 0xffff0000, v20
	s_waitcnt lgkmcnt(1)
	v_mul_f32_e32 v64, v24, v33
	v_lshlrev_b32_e32 v34, 16, v21
	v_mul_f32_e32 v61, v25, v20
	v_fmac_f32_e32 v77, v64, v64
	v_and_b32_e32 v21, 0xffff0000, v21
	v_mul_f32_e32 v57, v26, v34
	v_fmac_f32_e32 v77, v61, v61
	v_lshlrev_b32_e32 v36, 16, v22
	v_and_b32_e32 v22, 0xffff0000, v22
	v_lshlrev_b32_e32 v37, 16, v23
	v_and_b32_e32 v23, 0xffff0000, v23
	v_mul_f32_e32 v52, v27, v21
	v_fmac_f32_e32 v77, v57, v57
	s_waitcnt lgkmcnt(0)
	v_mul_f32_e32 v46, v28, v36
	v_mul_f32_e32 v41, v29, v22
	v_mul_f32_e32 v36, v30, v37
	v_mul_f32_e32 v30, v31, v23
	v_fmac_f32_e32 v77, v52, v52
	ds_read_b128 v[20:23], v76 offset:768
	ds_read_b128 v[24:27], v76 offset:784
	v_fmac_f32_e32 v77, v46, v46
	v_fmac_f32_e32 v77, v41, v41
	v_fmac_f32_e32 v77, v36, v36
	v_lshlrev_b32_e32 v28, 16, v16
	v_fmac_f32_e32 v77, v30, v30
	v_and_b32_e32 v16, 0xffff0000, v16
	s_waitcnt lgkmcnt(1)
	v_mul_f32_e32 v62, v20, v28
	v_lshlrev_b32_e32 v29, 16, v17
	v_mul_f32_e32 v58, v21, v16
	v_fmac_f32_e32 v77, v62, v62
	v_and_b32_e32 v17, 0xffff0000, v17
	v_mul_f32_e32 v53, v22, v29
	v_fmac_f32_e32 v77, v58, v58
	v_lshlrev_b32_e32 v31, 16, v18
	v_and_b32_e32 v18, 0xffff0000, v18
	v_lshlrev_b32_e32 v33, 16, v19
	v_and_b32_e32 v19, 0xffff0000, v19
	v_mul_f32_e32 v47, v23, v17
	v_fmac_f32_e32 v77, v53, v53
	s_waitcnt lgkmcnt(0)
	v_mul_f32_e32 v42, v24, v31
	v_mul_f32_e32 v37, v25, v18
	v_mul_f32_e32 v27, v27, v19
	v_fmac_f32_e32 v77, v47, v47
	ds_read_b128 v[16:19], v76 offset:1024
	ds_read_b128 v[20:23], v76 offset:1040
	v_fmac_f32_e32 v77, v42, v42
	v_mul_f32_e32 v31, v26, v33
	v_fmac_f32_e32 v77, v37, v37
	v_fmac_f32_e32 v77, v31, v31
	v_lshlrev_b32_e32 v24, 16, v12
	v_fmac_f32_e32 v77, v27, v27
	v_and_b32_e32 v12, 0xffff0000, v12
	s_waitcnt lgkmcnt(1)
	v_mul_f32_e32 v59, v16, v24
	v_lshlrev_b32_e32 v25, 16, v13
	v_mul_f32_e32 v54, v17, v12
	v_fmac_f32_e32 v77, v59, v59
	v_and_b32_e32 v13, 0xffff0000, v13
	v_mul_f32_e32 v48, v18, v25
	v_fmac_f32_e32 v77, v54, v54
	v_lshlrev_b32_e32 v26, 16, v14
	v_and_b32_e32 v14, 0xffff0000, v14
	v_lshlrev_b32_e32 v28, 16, v15
	v_and_b32_e32 v15, 0xffff0000, v15
	v_mul_f32_e32 v43, v19, v13
	v_fmac_f32_e32 v77, v48, v48
	s_waitcnt lgkmcnt(0)
	v_mul_f32_e32 v38, v20, v26
	v_mul_f32_e32 v33, v21, v14
	v_mul_f32_e32 v24, v23, v15
	v_fmac_f32_e32 v77, v43, v43
	ds_read_b128 v[12:15], v76 offset:1280
	ds_read_b128 v[16:19], v76 offset:1296
	v_fmac_f32_e32 v77, v38, v38
	v_mul_f32_e32 v28, v22, v28
	v_fmac_f32_e32 v77, v33, v33
	v_fmac_f32_e32 v77, v28, v28
	v_lshlrev_b32_e32 v20, 16, v8
	v_fmac_f32_e32 v77, v24, v24
	v_and_b32_e32 v8, 0xffff0000, v8
	s_waitcnt lgkmcnt(1)
	v_mul_f32_e32 v55, v12, v20
	v_lshlrev_b32_e32 v21, 16, v9
	v_mul_f32_e32 v49, v13, v8
	v_fmac_f32_e32 v77, v55, v55
	v_and_b32_e32 v9, 0xffff0000, v9
	v_mul_f32_e32 v44, v14, v21
	v_fmac_f32_e32 v77, v49, v49
	v_lshlrev_b32_e32 v22, 16, v10
	v_and_b32_e32 v10, 0xffff0000, v10
	v_lshlrev_b32_e32 v23, 16, v11
	v_and_b32_e32 v11, 0xffff0000, v11
	v_mul_f32_e32 v39, v15, v9
	v_fmac_f32_e32 v77, v44, v44
	s_waitcnt lgkmcnt(0)
	v_mul_f32_e32 v34, v16, v22
	v_mul_f32_e32 v29, v17, v10
	v_mul_f32_e32 v25, v18, v23
	v_mul_f32_e32 v23, v19, v11
	v_fmac_f32_e32 v77, v39, v39
	ds_read_b128 v[8:11], v76 offset:1536
	ds_read_b128 v[12:15], v76 offset:1552
	v_fmac_f32_e32 v77, v34, v34
	v_fmac_f32_e32 v77, v29, v29
	v_fmac_f32_e32 v77, v25, v25
	v_lshlrev_b32_e32 v16, 16, v4
	v_fmac_f32_e32 v77, v23, v23
	v_and_b32_e32 v4, 0xffff0000, v4
	s_waitcnt lgkmcnt(1)
	v_mul_f32_e32 v50, v8, v16
	v_lshlrev_b32_e32 v17, 16, v5
	v_and_b32_e32 v5, 0xffff0000, v5
	v_lshlrev_b32_e32 v18, 16, v6
	v_and_b32_e32 v6, 0xffff0000, v6
	v_lshlrev_b32_e32 v74, 16, v7
	v_and_b32_e32 v7, 0xffff0000, v7
	v_mul_f32_e32 v26, v9, v4
	v_fmac_f32_e32 v77, v50, v50
	v_mul_f32_e32 v22, v10, v17
	v_mul_f32_e32 v21, v11, v5
	s_waitcnt lgkmcnt(0)
	v_mul_f32_e32 v20, v12, v18
	v_mul_f32_e32 v19, v13, v6
	v_mul_f32_e32 v18, v14, v74
	v_mul_f32_e32 v17, v15, v7
	v_fmac_f32_e32 v77, v26, v26
	v_lshlrev_b32_e32 v4, 16, v0
	v_and_b32_e32 v5, 0xffff0000, v0
	v_lshlrev_b32_e32 v6, 16, v1
	v_and_b32_e32 v7, 0xffff0000, v1
	v_lshlrev_b32_e32 v8, 16, v2
	v_and_b32_e32 v9, 0xffff0000, v2
	v_lshlrev_b32_e32 v74, 16, v3
	v_and_b32_e32 v75, 0xffff0000, v3
	ds_read_b128 v[0:3], v76 offset:1792
	v_fmac_f32_e32 v77, v22, v22
	v_fmac_f32_e32 v77, v21, v21
	v_fmac_f32_e32 v77, v20, v20
	v_fmac_f32_e32 v77, v19, v19
	v_fmac_f32_e32 v77, v18, v18
	s_waitcnt lgkmcnt(0)
	v_pk_mul_f32 v[14:15], v[0:1], v[4:5]
	v_fmac_f32_e32 v77, v17, v17
	v_pk_mul_f32 v[0:1], v[14:15], v[14:15]
	v_pk_mul_f32 v[12:13], v[2:3], v[6:7]
	v_add_f32_e32 v0, v77, v0
	v_add_f32_e32 v4, v0, v1
	v_pk_mul_f32 v[0:1], v[12:13], v[12:13]
	s_lshl_b32 s0, s17, 2
	v_add_f32_e32 v0, v4, v0
	v_add_f32_e32 v4, v0, v1
	ds_read_b128 v[0:3], v76 offset:1808
	s_add_u32 s0, s52, s0
	s_addc_u32 s1, s53, 0
	s_waitcnt lgkmcnt(0)
	v_pk_mul_f32 v[10:11], v[0:1], v[8:9]
	s_nop 0
	v_pk_mul_f32 v[0:1], v[10:11], v[10:11]
	v_pk_mul_f32 v[8:9], v[2:3], v[74:75]
	v_add_f32_e32 v0, v4, v0
	v_add_f32_e32 v4, v0, v1
	v_pk_mul_f32 v[0:1], v[8:9], v[8:9]
	s_nop 0
	v_add_f32_e32 v0, v4, v0
	v_add_f32_e32 v0, v0, v1
	v_cndmask_b32_e32 v1, v185, v188, vcc
	v_lshlrev_b32_e32 v1, 2, v1
	ds_bpermute_b32 v1, v1, v0
	v_cmp_lt_i32_e32 vcc, v189, v187
	s_waitcnt lgkmcnt(0)
	v_add_f32_e32 v0, v0, v1
	v_cndmask_b32_e32 v1, v185, v189, vcc
	v_lshlrev_b32_e32 v1, 2, v1
	ds_bpermute_b32 v1, v1, v0
	v_cmp_lt_i32_e32 vcc, v190, v187
	s_waitcnt lgkmcnt(0)
	v_add_f32_e32 v0, v0, v1
	v_cndmask_b32_e32 v1, v185, v190, vcc
	v_lshlrev_b32_e32 v1, 2, v1
	ds_bpermute_b32 v1, v1, v0
	s_waitcnt lgkmcnt(0)
	v_add_f32_e32 v0, v0, v1
	v_fmamk_f32 v0, v0, 0x3b000000, v182
	v_cmp_gt_f32_e32 vcc, s56, v0
	v_mul_f32_e32 v1, 0x4b800000, v0
	s_nop 0
	v_cndmask_b32_e32 v0, v0, v1, vcc
	v_rsq_f32_e32 v0, v0
	s_nop 0
	v_mul_f32_e32 v1, 0x45800000, v0
	v_cndmask_b32_e32 v16, v0, v1, vcc
	global_load_dwordx4 v[142:145], v32, s[0:1] offset:1792
	v_mul_f32_e32 v73, v73, v16
	v_mul_f32_e32 v69, v69, v16
	v_mul_f32_e32 v68, v68, v16
	v_mul_f32_e32 v67, v67, v16
	v_mul_f32_e32 v72, v72, v16
	v_mul_f32_e32 v71, v71, v16
	v_mul_f32_e32 v70, v70, v16
	v_mul_f32_e32 v51, v51, v16
	v_mul_f32_e32 v60, v60, v16
	v_mul_f32_e32 v56, v56, v16
	v_mul_f32_e32 v20, v20, v16
	v_mul_f32_e32 v22, v22, v16
	v_mul_f32_e32 v21, v21, v16
	v_mul_f32_e32 v10, v10, v16
	v_mul_f32_e32 v12, v12, v16
	v_mul_f32_e32 v13, v13, v16
	s_waitcnt vmcnt(15)
	v_mul_f32_e32 v0, v204, v69
	s_waitcnt vmcnt(14)
	v_mul_f32_e32 v4, v208, v73
	v_mul_f32_e32 v1, v205, v68
	v_mul_f32_e32 v67, v206, v67
	v_mul_f32_e32 v2, v65, v16
	v_mul_f32_e32 v5, v209, v72
	v_mul_f32_e32 v65, v207, v2
	v_cvt_pk_bf16_f32 v2, v4, v5
	v_cvt_pk_bf16_f32 v4, v0, v1
	v_lshl_add_u64 v[0:1], s[8:9], 0, v[108:109]
	v_lshl_add_u64 v[0:1], v[0:1], 0, s[28:29]
	v_lshl_add_u64 v[0:1], v[0:1], 0, v[132:133]
	v_mul_f32_e32 v6, v210, v71
	v_mul_f32_e32 v7, v211, v70
	v_cvt_pk_bf16_f32 v3, v6, v7
	v_cvt_pk_bf16_f32 v5, v67, v65
	global_store_dwordx4 v[0:1], v[2:5], off
	v_mul_f32_e32 v6, v66, v16
	v_mul_f32_e32 v7, v63, v16
	s_waitcnt vmcnt(14)
	v_mul_f32_e32 v51, v51, v212
	v_mul_f32_e32 v2, v45, v16
	v_mul_f32_e32 v45, v2, v213
	v_mul_f32_e32 v2, v40, v16
	v_mul_f32_e32 v40, v2, v214
	v_mul_f32_e32 v2, v35, v16
	v_mul_f32_e32 v5, v2, v215
	s_waitcnt vmcnt(13)
	v_mul_f32_e32 v6, v6, v216
	v_mul_f32_e32 v7, v7, v217
	v_mul_f32_e32 v60, v60, v218
	v_mul_f32_e32 v56, v56, v219
	v_cvt_pk_bf16_f32 v2, v6, v7
	v_cvt_pk_bf16_f32 v3, v60, v56
	v_cvt_pk_bf16_f32 v4, v51, v45
	v_cvt_pk_bf16_f32 v5, v40, v5
	global_store_dwordx4 v[0:1], v[2:5], off offset:128
	v_mul_f32_e32 v45, v46, v16
	v_mul_f32_e32 v6, v64, v16
	v_mul_f32_e32 v7, v61, v16
	v_mul_f32_e32 v35, v57, v16
	v_mul_f32_e32 v40, v52, v16
	s_waitcnt vmcnt(13)
	v_mul_f32_e32 v45, v45, v220
	v_mul_f32_e32 v2, v41, v16
	v_mul_f32_e32 v41, v2, v221
	v_mul_f32_e32 v2, v36, v16
	v_mul_f32_e32 v36, v2, v222
	v_mul_f32_e32 v2, v30, v16
	v_mul_f32_e32 v5, v2, v223
	s_waitcnt vmcnt(12)
	v_mul_f32_e32 v6, v6, v224
	v_mul_f32_e32 v7, v7, v225
	v_mul_f32_e32 v35, v35, v226
	v_mul_f32_e32 v40, v40, v227
	v_cvt_pk_bf16_f32 v2, v6, v7
	v_cvt_pk_bf16_f32 v3, v35, v40
	v_cvt_pk_bf16_f32 v4, v45, v41
	v_cvt_pk_bf16_f32 v5, v36, v5
	global_store_dwordx4 v[0:1], v[2:5], off offset:256
	v_mul_f32_e32 v36, v42, v16
	v_mul_f32_e32 v6, v62, v16
	v_mul_f32_e32 v7, v58, v16
	v_mul_f32_e32 v30, v53, v16
	v_mul_f32_e32 v35, v47, v16
	s_waitcnt vmcnt(12)
	v_mul_f32_e32 v36, v36, v228
	v_mul_f32_e32 v2, v37, v16
	v_mul_f32_e32 v37, v2, v229
	v_mul_f32_e32 v2, v31, v16
	v_mul_f32_e32 v31, v2, v230
	v_mul_f32_e32 v2, v27, v16
	v_mul_f32_e32 v5, v2, v231
	s_waitcnt vmcnt(11)
	v_mul_f32_e32 v6, v6, v232
	v_mul_f32_e32 v7, v7, v233
	v_mul_f32_e32 v30, v30, v234
	v_mul_f32_e32 v35, v35, v235
	v_cvt_pk_bf16_f32 v2, v6, v7
	v_cvt_pk_bf16_f32 v3, v30, v35
	v_cvt_pk_bf16_f32 v4, v36, v37
	v_cvt_pk_bf16_f32 v5, v31, v5
	global_store_dwordx4 v[0:1], v[2:5], off offset:384
	v_mul_f32_e32 v31, v38, v16
	v_mul_f32_e32 v6, v59, v16
	v_mul_f32_e32 v7, v54, v16
	v_mul_f32_e32 v27, v48, v16
	v_mul_f32_e32 v30, v43, v16
	s_waitcnt vmcnt(11)
	v_mul_f32_e32 v31, v31, v236
	v_mul_f32_e32 v2, v33, v16
	v_mul_f32_e32 v33, v2, v237
	v_mul_f32_e32 v2, v28, v16
	v_mul_f32_e32 v28, v2, v238
	v_mul_f32_e32 v2, v24, v16
	v_mul_f32_e32 v5, v2, v239
	s_waitcnt vmcnt(10)
	v_mul_f32_e32 v6, v6, v240
	v_mul_f32_e32 v7, v7, v241
	v_mul_f32_e32 v27, v27, v242
	v_mul_f32_e32 v30, v30, v243
	v_cvt_pk_bf16_f32 v2, v6, v7
	v_cvt_pk_bf16_f32 v3, v27, v30
	v_cvt_pk_bf16_f32 v4, v31, v33
	v_cvt_pk_bf16_f32 v5, v28, v5
	global_store_dwordx4 v[0:1], v[2:5], off offset:512
	v_mul_f32_e32 v28, v34, v16
	v_mul_f32_e32 v6, v55, v16
	v_mul_f32_e32 v7, v49, v16
	v_mul_f32_e32 v24, v44, v16
	v_mul_f32_e32 v27, v39, v16
	s_waitcnt vmcnt(10)
	v_mul_f32_e32 v28, v28, v146
	v_mul_f32_e32 v2, v29, v16
	v_mul_f32_e32 v29, v2, v147
	v_mul_f32_e32 v2, v25, v16
	v_mul_f32_e32 v25, v2, v148
	v_mul_f32_e32 v2, v23, v16
	v_mul_f32_e32 v5, v2, v149
	s_waitcnt vmcnt(9)
	v_mul_f32_e32 v6, v6, v150
	v_mul_f32_e32 v7, v7, v151
	v_mul_f32_e32 v24, v24, v152
	v_mul_f32_e32 v27, v27, v153
	v_cvt_pk_bf16_f32 v2, v6, v7
	v_cvt_pk_bf16_f32 v3, v24, v27
	v_cvt_pk_bf16_f32 v4, v28, v29
	v_cvt_pk_bf16_f32 v5, v25, v5
	global_store_dwordx4 v[0:1], v[2:5], off offset:640
	v_mul_f32_e32 v6, v50, v16
	v_mul_f32_e32 v7, v26, v16
	s_waitcnt vmcnt(9)
	v_mul_f32_e32 v20, v20, v168
	v_mul_f32_e32 v2, v19, v16
	v_mul_f32_e32 v19, v2, v169
	v_mul_f32_e32 v2, v18, v16
	v_mul_f32_e32 v18, v2, v170
	v_mul_f32_e32 v2, v17, v16
	v_mul_f32_e32 v5, v2, v171
	s_waitcnt vmcnt(8)
	v_mul_f32_e32 v6, v6, v172
	v_mul_f32_e32 v7, v7, v173
	v_mul_f32_e32 v22, v22, v174
	v_mul_f32_e32 v21, v21, v175
	v_cvt_pk_bf16_f32 v2, v6, v7
	v_cvt_pk_bf16_f32 v3, v22, v21
	v_cvt_pk_bf16_f32 v4, v20, v19
	v_cvt_pk_bf16_f32 v5, v18, v5
	global_store_dwordx4 v[0:1], v[2:5], off offset:768
	v_mul_f32_e32 v6, v14, v16
	v_mul_f32_e32 v7, v15, v16
	s_mov_b64 s[0:1], 0
	s_waitcnt vmcnt(8)
	v_mul_f32_e32 v10, v10, v176
	v_mul_f32_e32 v2, v11, v16
	v_mul_f32_e32 v11, v2, v177
	v_mul_f32_e32 v2, v8, v16
	v_mul_f32_e32 v8, v2, v178
	v_mul_f32_e32 v2, v9, v16
	v_mul_f32_e32 v5, v2, v179
	s_waitcnt vmcnt(7)
	v_mul_f32_e32 v6, v6, v142
	v_mul_f32_e32 v7, v7, v143
	v_mul_f32_e32 v12, v12, v144
	v_mul_f32_e32 v13, v13, v145
	v_cvt_pk_bf16_f32 v2, v6, v7
	v_cvt_pk_bf16_f32 v3, v12, v13
	v_cvt_pk_bf16_f32 v4, v10, v11
	v_cvt_pk_bf16_f32 v5, v8, v5
	global_store_dwordx4 v[0:1], v[2:5], off offset:896
	s_barrier
